# grid-barrier poll interval s_sleep 1 -> 6 (fewer polling loads while stragglers finish)
# speedup vs baseline: 1.0021x; 1.0021x over previous
; DEV void grid_bar(unsigned* ctr, unsigned target) {
;   asm volatile("s_waitcnt vmcnt(0)" ::: "memory");
;   __syncthreads();
;   if (threadIdx.x == 0) {
;     __builtin_amdgcn_fence(__ATOMIC_RELEASE, "agent");
;     asm volatile("s_waitcnt vmcnt(0)" ::: "memory");
;     __hip_atomic_fetch_add(ctr, 1u, __ATOMIC_RELAXED, __HIP_MEMORY_SCOPE_AGENT);
;     while (__hip_atomic_load(ctr, __ATOMIC_RELAXED, __HIP_MEMORY_SCOPE_AGENT) < target) __builtin_amdgcn_s_sleep(1);
;     __builtin_amdgcn_fence(__ATOMIC_ACQUIRE, "agent");
;     asm volatile("s_waitcnt vmcnt(0)" ::: "memory");
;   }
;   __syncthreads();
; }
.LBB0_351:
	v_mov_b64_e32 v[0:1], s[4:5]
	s_sleep 6
	flat_load_dword v0, v[0:1] sc1
	s_waitcnt vmcnt(0) lgkmcnt(0)
	v_readfirstlane_b32 s11, v0
	s_cmp_ge_u32 s11, s10
	s_cselect_b64 s[12:13], -1, 0
	s_and_b64 s[12:13], exec, s[12:13]
	s_or_b64 s[8:9], s[12:13], s[8:9]
	s_andn2_b64 exec, exec, s[8:9]
	s_cbranch_execnz .LBB0_351
